# nt also on the B3 epilogue K-tile stores (537 MB/layer written once), on top of prep nt loads
# speedup vs baseline: 1.0018x; 1.0018x over previous
.LBB0_345:
	s_lshl_b32 s53, s24, 20
	s_lshl_b32 s56, s22, 17
	s_add_u32 s53, s53, s56
	s_add_u32 s54, s14, s53
	s_addc_u32 s55, s15, 0
	s_lshr_b32 s56, s24, 4
	s_lshl_b32 s56, s56, 4
	s_lshl_b32 s57, s22, 1
	s_add_i32 s56, s56, s57
	s_lshl_b32 s56, s56, 12
	s_and_b32 s57, s24, 15
	s_lshl_b32 s57, s57, 8
	s_add_i32 s56, s56, s57
	s_lshl_b32 s56, s56, 2
	s_add_u32 s58, s16, s56
	s_addc_u32 s59, s17, 0
	v_and_b32_e32 v145, 0xff, v0
	v_and_b32_e32 v146, 0x100, v0
	v_lshlrev_b32_e32 v145, 4, v145
	v_lshl_or_b32 v144, v146, 7, v145
	v_add_u32_e32 v172, 0x800, v144
	v_add_u32_e32 v173, 0x2000, v172
	v_add_u32_e32 v174, 0x4000, v172
	v_add_u32_e32 v175, 0x6000, v172
	v_add_u32_e32 v176, 0x10000, v172
	v_add_u32_e32 v177, 0x12000, v172
	v_add_u32_e32 v178, 0x14000, v172
	v_add_u32_e32 v179, 0x16000, v172
	v_and_b32_e32 v147, 0xc0, v0
	v_and_b32_e32 v149, 63, v0
	v_lshlrev_b32_e32 v147, 17, v147
	v_lshlrev_b32_e32 v149, 2, v149
	v_or3_b32 v147, v147, v146, v149
	v_add_u32_e32 v148, 0x4000, v147
	v_cvt_pk_bf16_f32 v152, v128, v129
	v_cvt_pk_bf16_f32 v153, v130, v131
	v_cvt_pk_bf16_f32 v154, v124, v125
	v_cvt_pk_bf16_f32 v155, v126, v127
	global_store_dwordx4 v172, v[152:155], s[54:55] offset:-2048 nt
	v_cvt_pk_bf16_f32 v156, v120, v121
	v_cvt_pk_bf16_f32 v157, v122, v123
	v_cvt_pk_bf16_f32 v158, v112, v113
	v_cvt_pk_bf16_f32 v159, v114, v115
	global_store_dwordx4 v172, v[156:159], s[54:55] offset:2048 nt
	v_cvt_pk_bf16_f32 v160, v116, v117
	v_cvt_pk_bf16_f32 v161, v118, v119
	v_cvt_pk_bf16_f32 v162, v108, v109
	v_cvt_pk_bf16_f32 v163, v110, v111
	global_store_dwordx4 v173, v[160:163], s[54:55] offset:-2048 nt
	v_cvt_pk_bf16_f32 v168, v104, v105
	v_cvt_pk_bf16_f32 v169, v106, v107
	v_cvt_pk_bf16_f32 v170, v96, v97
	v_cvt_pk_bf16_f32 v171, v98, v99
	global_store_dwordx4 v173, v[168:171], s[54:55] offset:2048 nt
	v_cvt_pk_bf16_f32 v152, v100, v101
	v_cvt_pk_bf16_f32 v153, v102, v103
	v_cvt_pk_bf16_f32 v154, v92, v93
	v_cvt_pk_bf16_f32 v155, v94, v95
	global_store_dwordx4 v174, v[152:155], s[54:55] offset:-2048 nt
	v_cvt_pk_bf16_f32 v156, v88, v89
	v_cvt_pk_bf16_f32 v157, v90, v91
	v_cvt_pk_bf16_f32 v158, v80, v81
	v_cvt_pk_bf16_f32 v159, v82, v83
	global_store_dwordx4 v174, v[156:159], s[54:55] offset:2048 nt
	v_cvt_pk_bf16_f32 v160, v84, v85
	v_cvt_pk_bf16_f32 v161, v86, v87
	v_cvt_pk_bf16_f32 v162, v76, v77
	v_cvt_pk_bf16_f32 v163, v78, v79
	global_store_dwordx4 v175, v[160:163], s[54:55] offset:-2048 nt
	v_cvt_pk_bf16_f32 v168, v72, v73
	v_cvt_pk_bf16_f32 v169, v74, v75
	v_cvt_pk_bf16_f32 v170, v68, v69
	v_cvt_pk_bf16_f32 v171, v70, v71
	global_store_dwordx4 v175, v[168:171], s[54:55] offset:2048 nt
	v_cvt_pk_bf16_f32 v152, v64, v65
	v_cvt_pk_bf16_f32 v153, v66, v67
	v_cvt_pk_bf16_f32 v154, v60, v61
	v_cvt_pk_bf16_f32 v155, v62, v63
	global_store_dwordx4 v176, v[152:155], s[54:55] offset:-2048 nt
	v_cvt_pk_bf16_f32 v156, v56, v57
	v_cvt_pk_bf16_f32 v157, v58, v59
	v_cvt_pk_bf16_f32 v158, v48, v49
	v_cvt_pk_bf16_f32 v159, v50, v51
	global_store_dwordx4 v176, v[156:159], s[54:55] offset:2048 nt
	v_cvt_pk_bf16_f32 v160, v52, v53
	v_cvt_pk_bf16_f32 v161, v54, v55
	v_cvt_pk_bf16_f32 v162, v44, v45
	v_cvt_pk_bf16_f32 v163, v46, v47
	global_store_dwordx4 v177, v[160:163], s[54:55] offset:-2048 nt
	v_cvt_pk_bf16_f32 v168, v40, v41
	v_cvt_pk_bf16_f32 v169, v42, v43
	v_cvt_pk_bf16_f32 v170, v32, v33
	v_cvt_pk_bf16_f32 v171, v34, v35
	global_store_dwordx4 v177, v[168:171], s[54:55] offset:2048 nt
	v_cvt_pk_bf16_f32 v152, v36, v37
	v_cvt_pk_bf16_f32 v153, v38, v39
	v_cvt_pk_bf16_f32 v154, v28, v29
	v_cvt_pk_bf16_f32 v155, v30, v31
	global_store_dwordx4 v178, v[152:155], s[54:55] offset:-2048 nt
	v_cvt_pk_bf16_f32 v156, v24, v25
	v_cvt_pk_bf16_f32 v157, v26, v27
	v_cvt_pk_bf16_f32 v158, v16, v17
	v_cvt_pk_bf16_f32 v159, v18, v19
	global_store_dwordx4 v178, v[156:159], s[54:55] offset:2048 nt
	v_cvt_pk_bf16_f32 v160, v20, v21
	v_cvt_pk_bf16_f32 v161, v22, v23
	v_cvt_pk_bf16_f32 v162, v12, v13
	v_cvt_pk_bf16_f32 v163, v14, v15
	global_store_dwordx4 v179, v[160:163], s[54:55] offset:-2048 nt
	v_cvt_pk_bf16_f32 v168, v8, v9
	v_cvt_pk_bf16_f32 v169, v10, v11
	v_cvt_pk_bf16_f32 v170, v4, v5
	v_cvt_pk_bf16_f32 v171, v6, v7
	global_store_dwordx4 v179, v[168:171], s[54:55] offset:2048 nt
	v_mul_f32_e32 v180, v128, v128
	v_mul_f32_e32 v181, v116, v116
	v_mul_f32_e32 v182, v100, v100
	v_mul_f32_e32 v183, v84, v84
	v_fmac_f32_e32 v180, v129, v129
	v_fmac_f32_e32 v181, v117, v117
	v_fmac_f32_e32 v182, v101, v101
	v_fmac_f32_e32 v183, v85, v85
	v_fmac_f32_e32 v180, v130, v130
	v_fmac_f32_e32 v181, v118, v118
	v_fmac_f32_e32 v182, v102, v102
	v_fmac_f32_e32 v183, v86, v86
	v_fmac_f32_e32 v180, v131, v131
	v_fmac_f32_e32 v181, v119, v119
	v_fmac_f32_e32 v182, v103, v103
	v_fmac_f32_e32 v183, v87, v87
	v_fmac_f32_e32 v180, v124, v124
	v_fmac_f32_e32 v181, v108, v108
	v_fmac_f32_e32 v182, v92, v92
	v_fmac_f32_e32 v183, v76, v76
	v_fmac_f32_e32 v180, v125, v125
	v_fmac_f32_e32 v181, v109, v109
	v_fmac_f32_e32 v182, v93, v93
	v_fmac_f32_e32 v183, v77, v77
	v_fmac_f32_e32 v180, v126, v126
	v_fmac_f32_e32 v181, v110, v110
	v_fmac_f32_e32 v182, v94, v94
	v_fmac_f32_e32 v183, v78, v78
	v_fmac_f32_e32 v180, v127, v127
	v_fmac_f32_e32 v181, v111, v111
	v_fmac_f32_e32 v182, v95, v95
	v_fmac_f32_e32 v183, v79, v79
	v_mul_f32_e32 v184, v120, v120
	v_mul_f32_e32 v185, v104, v104
	v_mul_f32_e32 v186, v88, v88
	v_mul_f32_e32 v187, v72, v72
	v_fmac_f32_e32 v184, v121, v121
	v_fmac_f32_e32 v185, v105, v105
	v_fmac_f32_e32 v186, v89, v89
	v_fmac_f32_e32 v187, v73, v73
	v_fmac_f32_e32 v184, v122, v122
	v_fmac_f32_e32 v185, v106, v106
	v_fmac_f32_e32 v186, v90, v90
	v_fmac_f32_e32 v187, v74, v74
	v_fmac_f32_e32 v184, v123, v123
	v_fmac_f32_e32 v185, v107, v107
	v_fmac_f32_e32 v186, v91, v91
	v_fmac_f32_e32 v187, v75, v75
	v_fmac_f32_e32 v184, v112, v112
	v_fmac_f32_e32 v185, v96, v96
	v_fmac_f32_e32 v186, v80, v80
	v_fmac_f32_e32 v187, v68, v68
	v_fmac_f32_e32 v184, v113, v113
	v_fmac_f32_e32 v185, v97, v97
	v_fmac_f32_e32 v186, v81, v81
	v_fmac_f32_e32 v187, v69, v69
	v_fmac_f32_e32 v184, v114, v114
	v_fmac_f32_e32 v185, v98, v98
	v_fmac_f32_e32 v186, v82, v82
	v_fmac_f32_e32 v187, v70, v70
	v_fmac_f32_e32 v184, v115, v115
	v_fmac_f32_e32 v185, v99, v99
	v_fmac_f32_e32 v186, v83, v83
	v_fmac_f32_e32 v187, v71, v71
	v_mul_f32_e32 v188, v64, v64
	v_mul_f32_e32 v189, v52, v52
	v_mul_f32_e32 v190, v36, v36
	v_mul_f32_e32 v191, v20, v20
	v_fmac_f32_e32 v188, v65, v65
	v_fmac_f32_e32 v189, v53, v53
	v_fmac_f32_e32 v190, v37, v37
	v_fmac_f32_e32 v191, v21, v21
	v_fmac_f32_e32 v188, v66, v66
	v_fmac_f32_e32 v189, v54, v54
	v_fmac_f32_e32 v190, v38, v38
	v_fmac_f32_e32 v191, v22, v22
	v_fmac_f32_e32 v188, v67, v67
	v_fmac_f32_e32 v189, v55, v55
	v_fmac_f32_e32 v190, v39, v39
	v_fmac_f32_e32 v191, v23, v23
	v_fmac_f32_e32 v188, v60, v60
	v_fmac_f32_e32 v189, v44, v44
	v_fmac_f32_e32 v190, v28, v28
	v_fmac_f32_e32 v191, v12, v12
	v_fmac_f32_e32 v188, v61, v61
	v_fmac_f32_e32 v189, v45, v45
	v_fmac_f32_e32 v190, v29, v29
	v_fmac_f32_e32 v191, v13, v13
	v_fmac_f32_e32 v188, v62, v62
	v_fmac_f32_e32 v189, v46, v46
	v_fmac_f32_e32 v190, v30, v30
	v_fmac_f32_e32 v191, v14, v14
	v_fmac_f32_e32 v188, v63, v63
	v_fmac_f32_e32 v189, v47, v47
	v_fmac_f32_e32 v190, v31, v31
	v_fmac_f32_e32 v191, v15, v15
	v_mul_f32_e32 v192, v56, v56
	v_mul_f32_e32 v193, v40, v40
	v_mul_f32_e32 v194, v24, v24
	v_mul_f32_e32 v195, v8, v8
	v_fmac_f32_e32 v192, v57, v57
	v_fmac_f32_e32 v193, v41, v41
	v_fmac_f32_e32 v194, v25, v25
	v_fmac_f32_e32 v195, v9, v9
	v_fmac_f32_e32 v192, v58, v58
	v_fmac_f32_e32 v193, v42, v42
	v_fmac_f32_e32 v194, v26, v26
	v_fmac_f32_e32 v195, v10, v10
	v_fmac_f32_e32 v192, v59, v59
	v_fmac_f32_e32 v193, v43, v43
	v_fmac_f32_e32 v194, v27, v27
	v_fmac_f32_e32 v195, v11, v11
	v_fmac_f32_e32 v192, v48, v48
	v_fmac_f32_e32 v193, v32, v32
	v_fmac_f32_e32 v194, v16, v16
	v_fmac_f32_e32 v195, v4, v4
	v_fmac_f32_e32 v192, v49, v49
	v_fmac_f32_e32 v193, v33, v33
	v_fmac_f32_e32 v194, v17, v17
	v_fmac_f32_e32 v195, v5, v5
	v_fmac_f32_e32 v192, v50, v50
	v_fmac_f32_e32 v193, v34, v34
	v_fmac_f32_e32 v194, v18, v18
	v_fmac_f32_e32 v195, v6, v6
	v_fmac_f32_e32 v192, v51, v51
	v_fmac_f32_e32 v193, v35, v35
	v_fmac_f32_e32 v194, v19, v19
	v_fmac_f32_e32 v195, v7, v7
	v_permlane32_swap_b32_e32 v180, v182
	v_permlane32_swap_b32_e32 v181, v183
	v_permlane32_swap_b32_e32 v184, v186
	v_permlane32_swap_b32_e32 v185, v187
	v_permlane32_swap_b32_e32 v188, v190
	v_permlane32_swap_b32_e32 v189, v191
	v_permlane32_swap_b32_e32 v192, v194
	v_permlane32_swap_b32_e32 v193, v195
	v_add_f32_e32 v180, v180, v182
	v_add_f32_e32 v181, v181, v183
	v_add_f32_e32 v184, v184, v186
	v_add_f32_e32 v185, v185, v187
	v_add_f32_e32 v188, v188, v190
	v_add_f32_e32 v189, v189, v191
	v_add_f32_e32 v192, v192, v194
	v_add_f32_e32 v193, v193, v195
	s_nop 1
	v_permlane16_swap_b32_e32 v180, v181
	v_permlane16_swap_b32_e32 v184, v185
	v_permlane16_swap_b32_e32 v188, v189
	v_permlane16_swap_b32_e32 v192, v193
	v_add_f32_e32 v180, v180, v181
	v_add_f32_e32 v184, v184, v185
	v_add_f32_e32 v188, v188, v189
	v_add_f32_e32 v192, v192, v193
	global_store_dword v147, v180, s[58:59]
	global_store_dword v148, v184, s[58:59]
	global_store_dword v147, v188, s[58:59] offset:512
	global_store_dword v148, v192, s[58:59] offset:512
	s_andn2_b64 vcc, exec, s[42:43]
	s_mov_b64 s[22:23], -1
	s_cbranch_vccnz .LBB0_334
	s_andn2_b64 vcc, exec, s[12:13]
	s_cbranch_vccnz .LBB0_333
	s_barrier
	s_branch .LBB0_333
